# gated-residual GEMM epilogues: batch 8 global loads per row group with counted vmcnt waits instead of flat load/wait(0)/store ladder
# speedup vs baseline: 1.0049x; 1.0006x over previous
;     __device__ __forceinline__ void operator()(const pg8::f32x4 (&acc)[2][2][4][2], const pg8::Unit& u, int wr, int wc, int fr, int fq) const {
;         const int col0 = u.pn * 256 + wc * 32 + 4 * fq;
; #pragma unroll
;         for (int ai = 0; ai < 2; ++ai)
; #pragma unroll
;             for (int m = 0; m < 4; ++m) {
;                 const int r = row_off + u.pm * 256 + ai * 128 + wr * 64 + m * 16 + fr;
;                 const bool lat = r < ML; const int bi = lat ? (r >> 13) : 4;
;                 const size_t off = lat ? (size_t)r * 1024 : (size_t)(r - ML) * 1024;
;                 const float* bp = (lat ? base_lat : base_ctx) + off + col0; float* op = (lat ? out_lat : out_ctx) + off + col0;
;                 const float* gp = gate + bi * 6144 + col0;
; #pragma unroll
;                 for (int bj = 0; bj < 2; ++bj)
; #pragma unroll
;                     for (int n = 0; n < 2; ++n) {
;                         const pg8::f32x4 g4 = *(const pg8::f32x4*)(gp + bj * 128 + n * 16), b4 = *(const pg8::f32x4*)(bp + bj * 128 + n * 16);
;                         *(pg8::f32x4*)(op + bj * 128 + n * 16) = b4 + g4 * acc[ai][bj][m][n];
;                     }
;             }
;     }
.LBB0_921:
	v_lshl_add_u32 v142, s46, 8, v136
	v_min_i32_e32 v140, 0x8000, v142
	v_cmp_gt_i32_e32 vcc, s97, v142
	v_ashrrev_i32_e32 v154, 13, v140
	v_ashrrev_i32_e32 v140, 31, v142
	v_add_u32_e32 v141, 0xffff8000, v142
	v_lshl_or_b32 v134, s47, 8, v138
	v_cndmask_b32_e32 v147, 0, v140, vcc
	v_cndmask_b32_e32 v146, v141, v142, vcc
	v_mov_b32_e32 v140, s3
	v_mov_b32_e32 v141, s53
	v_mov_b32_e32 v143, s2
	v_mov_b32_e32 v144, s52
	v_ashrrev_i32_e32 v135, 31, v134
	v_cndmask_b32_e32 v149, v140, v141, vcc
	v_cndmask_b32_e32 v148, v143, v144, vcc
	v_lshlrev_b64 v[150:151], 12, v[146:147]
	v_readlane_b32 s12, v254, 35
	v_lshl_add_u64 v[146:147], v[148:149], 0, v[150:151]
	v_lshlrev_b64 v[134:135], 2, v[134:135]
	v_readlane_b32 s13, v254, 36
	v_lshl_add_u64 v[158:159], v[146:147], 0, v[134:135]
	v_mov_b32_e32 v145, s76
	v_mov_b32_e32 v146, s13
	v_mov_b32_e32 v147, s75
	v_mov_b32_e32 v148, s12
	v_cndmask_b32_e32 v153, v145, v146, vcc
	v_cndmask_b32_e32 v152, v147, v148, vcc
	v_lshl_add_u64 v[150:151], v[152:153], 0, v[150:151]
	v_lshl_add_u64 v[160:161], v[150:151], 0, v[134:135]
	v_mul_i32_i24_e32 v150, 0x1800, v154
	v_ashrrev_i32_e32 v151, 31, v150
	v_lshl_add_u64 v[150:151], v[150:151], 2, s[6:7]
	v_lshl_add_u64 v[162:163], v[150:151], 0, v[134:135]
	global_load_dwordx4 v[164:167], v[162:163], off
	global_load_dwordx4 v[168:171], v[158:159], off
	global_load_dwordx4 v[172:175], v[162:163], off offset:64
	global_load_dwordx4 v[176:179], v[158:159], off offset:64
	global_load_dwordx4 v[180:183], v[162:163], off offset:512
	global_load_dwordx4 v[184:187], v[158:159], off offset:512
	global_load_dwordx4 v[188:191], v[162:163], off offset:576
	global_load_dwordx4 v[192:195], v[158:159], off offset:576
	s_mov_b64 s[46:47], -1
	v_readlane_b32 s79, v254, 48
	v_readlane_b32 s83, v254, 49
	s_mov_b32 s87, 0xbfc90fda
	s_brev_b32 s88, 1
	s_waitcnt vmcnt(6) lgkmcnt(0)
	v_pk_fma_f32 v[126:127], v[126:127], v[166:167], v[170:171]
	v_pk_fma_f32 v[124:125], v[124:125], v[164:165], v[168:169]
	global_store_dwordx4 v[160:161], v[124:127], off
	s_waitcnt vmcnt(5) lgkmcnt(0)
	v_pk_fma_f32 v[122:123], v[122:123], v[174:175], v[178:179]
	v_pk_fma_f32 v[120:121], v[120:121], v[172:173], v[176:177]
	global_store_dwordx4 v[160:161], v[120:123], off offset:64
	s_waitcnt vmcnt(4) lgkmcnt(0)
	v_pk_fma_f32 v[118:119], v[118:119], v[182:183], v[186:187]
	v_pk_fma_f32 v[116:117], v[116:117], v[180:181], v[184:185]
	global_store_dwordx4 v[160:161], v[116:119], off offset:512
	s_waitcnt vmcnt(3) lgkmcnt(0)
	v_pk_fma_f32 v[114:115], v[114:115], v[190:191], v[194:195]
	v_pk_fma_f32 v[112:113], v[112:113], v[188:189], v[192:193]
	global_store_dwordx4 v[160:161], v[112:115], off offset:576
	s_nop 1
	v_or_b32_e32 v112, 16, v142
	v_min_i32_e32 v113, 0x8000, v112
	v_cmp_gt_i32_e32 vcc, s97, v112
	v_ashrrev_i32_e32 v116, 13, v113
	v_ashrrev_i32_e32 v113, 31, v112
	v_add_u32_e32 v114, 0xffff8010, v142
	v_cndmask_b32_e32 v113, 0, v113, vcc
	v_cndmask_b32_e32 v112, v114, v112, vcc
	v_cndmask_b32_e32 v115, v140, v141, vcc
	v_cndmask_b32_e32 v114, v143, v144, vcc
	v_lshlrev_b64 v[112:113], 12, v[112:113]
	v_lshl_add_u64 v[114:115], v[114:115], 0, v[112:113]
	v_lshl_add_u64 v[120:121], v[114:115], 0, v[134:135]
	v_cndmask_b32_e32 v115, v145, v146, vcc
	v_cndmask_b32_e32 v114, v147, v148, vcc
	v_lshl_add_u64 v[112:113], v[114:115], 0, v[112:113]
	v_lshl_add_u64 v[122:123], v[112:113], 0, v[134:135]
	v_mul_i32_i24_e32 v112, 0x1800, v116
	v_ashrrev_i32_e32 v113, 31, v112
	v_lshl_add_u64 v[112:113], v[112:113], 2, s[6:7]
	v_lshl_add_u64 v[124:125], v[112:113], 0, v[134:135]
	global_load_dwordx4 v[164:167], v[124:125], off
	global_load_dwordx4 v[168:171], v[120:121], off
	global_load_dwordx4 v[172:175], v[124:125], off offset:64
	global_load_dwordx4 v[176:179], v[120:121], off offset:64
	global_load_dwordx4 v[180:183], v[124:125], off offset:512
	global_load_dwordx4 v[184:187], v[120:121], off offset:512
	global_load_dwordx4 v[188:191], v[124:125], off offset:576
	global_load_dwordx4 v[192:195], v[120:121], off offset:576
	s_waitcnt vmcnt(6) lgkmcnt(0)
	v_pk_fma_f32 v[110:111], v[110:111], v[166:167], v[170:171]
	v_pk_fma_f32 v[108:109], v[108:109], v[164:165], v[168:169]
	global_store_dwordx4 v[122:123], v[108:111], off
	s_waitcnt vmcnt(5) lgkmcnt(0)
	v_pk_fma_f32 v[106:107], v[106:107], v[174:175], v[178:179]
	v_pk_fma_f32 v[104:105], v[104:105], v[172:173], v[176:177]
	global_store_dwordx4 v[122:123], v[104:107], off offset:64
	s_waitcnt vmcnt(4) lgkmcnt(0)
	v_pk_fma_f32 v[102:103], v[102:103], v[182:183], v[186:187]
	v_pk_fma_f32 v[100:101], v[100:101], v[180:181], v[184:185]
	global_store_dwordx4 v[122:123], v[100:103], off offset:512
	s_waitcnt vmcnt(3) lgkmcnt(0)
	v_pk_fma_f32 v[98:99], v[98:99], v[190:191], v[194:195]
	v_pk_fma_f32 v[96:97], v[96:97], v[188:189], v[192:193]
	global_store_dwordx4 v[122:123], v[96:99], off offset:576
	s_nop 1
	v_or_b32_e32 v96, 32, v142
	v_min_i32_e32 v97, 0x8000, v96
	v_cmp_gt_i32_e32 vcc, s97, v96
	v_ashrrev_i32_e32 v100, 13, v97
	v_ashrrev_i32_e32 v97, 31, v96
	v_add_u32_e32 v98, 0xffff8020, v142
	v_cndmask_b32_e32 v97, 0, v97, vcc
	v_cndmask_b32_e32 v96, v98, v96, vcc
	v_cndmask_b32_e32 v99, v140, v141, vcc
	v_cndmask_b32_e32 v98, v143, v144, vcc
	v_lshlrev_b64 v[96:97], 12, v[96:97]
	v_lshl_add_u64 v[98:99], v[98:99], 0, v[96:97]
	v_lshl_add_u64 v[104:105], v[98:99], 0, v[134:135]
	v_cndmask_b32_e32 v99, v145, v146, vcc
	v_cndmask_b32_e32 v98, v147, v148, vcc
	v_lshl_add_u64 v[96:97], v[98:99], 0, v[96:97]
	v_lshl_add_u64 v[106:107], v[96:97], 0, v[134:135]
	v_mul_i32_i24_e32 v96, 0x1800, v100
	v_ashrrev_i32_e32 v97, 31, v96
	v_lshl_add_u64 v[96:97], v[96:97], 2, s[6:7]
	v_lshl_add_u64 v[108:109], v[96:97], 0, v[134:135]
	global_load_dwordx4 v[164:167], v[108:109], off
	global_load_dwordx4 v[168:171], v[104:105], off
	global_load_dwordx4 v[172:175], v[108:109], off offset:64
	global_load_dwordx4 v[176:179], v[104:105], off offset:64
	global_load_dwordx4 v[180:183], v[108:109], off offset:512
	global_load_dwordx4 v[184:187], v[104:105], off offset:512
	global_load_dwordx4 v[188:191], v[108:109], off offset:576
	global_load_dwordx4 v[192:195], v[104:105], off offset:576
	s_waitcnt vmcnt(6) lgkmcnt(0)
;     __device__ __forceinline__ void operator()(const pg8::f32x4 (&acc)[2][2][4][2], const pg8::Unit& u, int wr, int wc, int fr, int fq) const {
;         const int col0 = u.pn * 256 + wc * 32 + 4 * fq;
; #pragma unroll
;         for (int ai = 0; ai < 2; ++ai)
; #pragma unroll
;             for (int m = 0; m < 4; ++m) {
;                 const int r = row_off + u.pm * 256 + ai * 128 + wr * 64 + m * 16 + fr;
;                 const bool lat = r < ML; const int bi = lat ? (r >> 13) : 4;
;                 const size_t off = lat ? (size_t)r * 1024 : (size_t)(r - ML) * 1024;
;                 const float* bp = (lat ? base_lat : base_ctx) + off + col0; float* op = (lat ? out_lat : out_ctx) + off + col0;
;                 const float* gp = gate + bi * 6144 + col0;
; #pragma unroll
;                 for (int bj = 0; bj < 2; ++bj)
; #pragma unroll
;                     for (int n = 0; n < 2; ++n) {
;                         const pg8::f32x4 g4 = *(const pg8::f32x4*)(gp + bj * 128 + n * 16), b4 = *(const pg8::f32x4*)(bp + bj * 128 + n * 16);
;                         *(pg8::f32x4*)(op + bj * 128 + n * 16) = b4 + g4 * acc[ai][bj][m][n];
;                     }
;             }
;     }
	v_pk_fma_f32 v[94:95], v[94:95], v[166:167], v[170:171]
	v_pk_fma_f32 v[92:93], v[92:93], v[164:165], v[168:169]
	global_store_dwordx4 v[106:107], v[92:95], off
	s_waitcnt vmcnt(5) lgkmcnt(0)
	v_pk_fma_f32 v[90:91], v[90:91], v[174:175], v[178:179]
	v_pk_fma_f32 v[88:89], v[88:89], v[172:173], v[176:177]
	global_store_dwordx4 v[106:107], v[88:91], off offset:64
	s_waitcnt vmcnt(4) lgkmcnt(0)
	v_pk_fma_f32 v[86:87], v[86:87], v[182:183], v[186:187]
	v_pk_fma_f32 v[84:85], v[84:85], v[180:181], v[184:185]
	global_store_dwordx4 v[106:107], v[84:87], off offset:512
	s_waitcnt vmcnt(3) lgkmcnt(0)
	v_pk_fma_f32 v[82:83], v[82:83], v[190:191], v[194:195]
	v_pk_fma_f32 v[80:81], v[80:81], v[188:189], v[192:193]
	global_store_dwordx4 v[106:107], v[80:83], off offset:576
	s_nop 1
	v_or_b32_e32 v80, 48, v142
	v_min_i32_e32 v81, 0x8000, v80
	v_cmp_gt_i32_e32 vcc, s97, v80
	v_ashrrev_i32_e32 v84, 13, v81
	v_ashrrev_i32_e32 v81, 31, v80
	v_add_u32_e32 v82, 0xffff8030, v142
	v_cndmask_b32_e32 v81, 0, v81, vcc
	v_cndmask_b32_e32 v80, v82, v80, vcc
	v_cndmask_b32_e32 v83, v140, v141, vcc
	v_cndmask_b32_e32 v82, v143, v144, vcc
	v_lshlrev_b64 v[80:81], 12, v[80:81]
	v_lshl_add_u64 v[82:83], v[82:83], 0, v[80:81]
	v_lshl_add_u64 v[88:89], v[82:83], 0, v[134:135]
	v_cndmask_b32_e32 v83, v145, v146, vcc
	v_cndmask_b32_e32 v82, v147, v148, vcc
	v_lshl_add_u64 v[80:81], v[82:83], 0, v[80:81]
	v_lshl_add_u64 v[90:91], v[80:81], 0, v[134:135]
	v_mul_i32_i24_e32 v80, 0x1800, v84
	v_ashrrev_i32_e32 v81, 31, v80
	v_lshl_add_u64 v[80:81], v[80:81], 2, s[6:7]
	v_lshl_add_u64 v[92:93], v[80:81], 0, v[134:135]
	global_load_dwordx4 v[164:167], v[92:93], off
	global_load_dwordx4 v[168:171], v[88:89], off
	global_load_dwordx4 v[172:175], v[92:93], off offset:64
	global_load_dwordx4 v[176:179], v[88:89], off offset:64
	global_load_dwordx4 v[180:183], v[92:93], off offset:512
	global_load_dwordx4 v[184:187], v[88:89], off offset:512
	global_load_dwordx4 v[188:191], v[92:93], off offset:576
	global_load_dwordx4 v[192:195], v[88:89], off offset:576
	s_waitcnt vmcnt(6) lgkmcnt(0)
	v_pk_fma_f32 v[78:79], v[78:79], v[166:167], v[170:171]
	v_pk_fma_f32 v[76:77], v[76:77], v[164:165], v[168:169]
	global_store_dwordx4 v[90:91], v[76:79], off
	s_waitcnt vmcnt(5) lgkmcnt(0)
	v_pk_fma_f32 v[74:75], v[74:75], v[174:175], v[178:179]
	v_pk_fma_f32 v[72:73], v[72:73], v[172:173], v[176:177]
	global_store_dwordx4 v[90:91], v[72:75], off offset:64
	s_waitcnt vmcnt(4) lgkmcnt(0)
	v_pk_fma_f32 v[70:71], v[70:71], v[182:183], v[186:187]
	v_pk_fma_f32 v[68:69], v[68:69], v[180:181], v[184:185]
	global_store_dwordx4 v[90:91], v[68:71], off offset:512
	s_waitcnt vmcnt(3) lgkmcnt(0)
	v_pk_fma_f32 v[66:67], v[66:67], v[190:191], v[194:195]
	v_pk_fma_f32 v[64:65], v[64:65], v[188:189], v[192:193]
	global_store_dwordx4 v[90:91], v[64:67], off offset:576
	s_nop 1
	v_add_u32_e32 v64, 0x80, v142
	v_min_i32_e32 v65, 0x8000, v64
	v_cmp_gt_i32_e32 vcc, s97, v64
	v_ashrrev_i32_e32 v68, 13, v65
	v_ashrrev_i32_e32 v65, 31, v64
	v_add_u32_e32 v66, 0xffff8080, v142
	v_cndmask_b32_e32 v65, 0, v65, vcc
	v_cndmask_b32_e32 v64, v66, v64, vcc
	v_cndmask_b32_e32 v67, v140, v141, vcc
	v_cndmask_b32_e32 v66, v143, v144, vcc
	v_lshlrev_b64 v[64:65], 12, v[64:65]
	v_lshl_add_u64 v[66:67], v[66:67], 0, v[64:65]
	v_lshl_add_u64 v[72:73], v[66:67], 0, v[134:135]
	v_cndmask_b32_e32 v67, v145, v146, vcc
	v_cndmask_b32_e32 v66, v147, v148, vcc
	v_lshl_add_u64 v[64:65], v[66:67], 0, v[64:65]
	v_lshl_add_u64 v[74:75], v[64:65], 0, v[134:135]
	v_mul_i32_i24_e32 v64, 0x1800, v68
	v_ashrrev_i32_e32 v65, 31, v64
	v_lshl_add_u64 v[64:65], v[64:65], 2, s[6:7]
	v_lshl_add_u64 v[76:77], v[64:65], 0, v[134:135]
	global_load_dwordx4 v[164:167], v[76:77], off
	global_load_dwordx4 v[168:171], v[72:73], off
	global_load_dwordx4 v[172:175], v[76:77], off offset:64
	global_load_dwordx4 v[176:179], v[72:73], off offset:64
	global_load_dwordx4 v[180:183], v[76:77], off offset:512
	global_load_dwordx4 v[184:187], v[72:73], off offset:512
	global_load_dwordx4 v[188:191], v[76:77], off offset:576
	global_load_dwordx4 v[192:195], v[72:73], off offset:576
	s_waitcnt vmcnt(6) lgkmcnt(0)
	v_pk_fma_f32 v[62:63], v[62:63], v[166:167], v[170:171]
	v_pk_fma_f32 v[60:61], v[60:61], v[164:165], v[168:169]
	global_store_dwordx4 v[74:75], v[60:63], off
	s_waitcnt vmcnt(5) lgkmcnt(0)
	v_pk_fma_f32 v[58:59], v[58:59], v[174:175], v[178:179]
	v_pk_fma_f32 v[56:57], v[56:57], v[172:173], v[176:177]
	global_store_dwordx4 v[74:75], v[56:59], off offset:64
	s_waitcnt vmcnt(4) lgkmcnt(0)
	v_pk_fma_f32 v[54:55], v[54:55], v[182:183], v[186:187]
	v_pk_fma_f32 v[52:53], v[52:53], v[180:181], v[184:185]
	global_store_dwordx4 v[74:75], v[52:55], off offset:512
	s_waitcnt vmcnt(3) lgkmcnt(0)
	v_pk_fma_f32 v[50:51], v[50:51], v[190:191], v[194:195]
	v_pk_fma_f32 v[48:49], v[48:49], v[188:189], v[192:193]
	global_store_dwordx4 v[74:75], v[48:51], off offset:576
	s_nop 1
	v_add_u32_e32 v48, 0x90, v142
	v_min_i32_e32 v49, 0x8000, v48
	v_cmp_gt_i32_e32 vcc, s97, v48
	v_ashrrev_i32_e32 v52, 13, v49
	v_ashrrev_i32_e32 v49, 31, v48
	v_add_u32_e32 v50, 0xffff8090, v142
	v_cndmask_b32_e32 v49, 0, v49, vcc
	v_cndmask_b32_e32 v48, v50, v48, vcc
	v_cndmask_b32_e32 v51, v140, v141, vcc
	v_cndmask_b32_e32 v50, v143, v144, vcc
	v_lshlrev_b64 v[48:49], 12, v[48:49]
	v_lshl_add_u64 v[50:51], v[50:51], 0, v[48:49]
	v_lshl_add_u64 v[56:57], v[50:51], 0, v[134:135]
	v_cndmask_b32_e32 v51, v145, v146, vcc
	v_cndmask_b32_e32 v50, v147, v148, vcc
	v_lshl_add_u64 v[48:49], v[50:51], 0, v[48:49]
	v_lshl_add_u64 v[58:59], v[48:49], 0, v[134:135]
	v_mul_i32_i24_e32 v48, 0x1800, v52
	v_ashrrev_i32_e32 v49, 31, v48
	v_lshl_add_u64 v[48:49], v[48:49], 2, s[6:7]
	v_lshl_add_u64 v[60:61], v[48:49], 0, v[134:135]
	global_load_dwordx4 v[164:167], v[60:61], off
	global_load_dwordx4 v[168:171], v[56:57], off
	global_load_dwordx4 v[172:175], v[60:61], off offset:64
	global_load_dwordx4 v[176:179], v[56:57], off offset:64
	global_load_dwordx4 v[180:183], v[60:61], off offset:512
	global_load_dwordx4 v[184:187], v[56:57], off offset:512
	global_load_dwordx4 v[188:191], v[60:61], off offset:576
	global_load_dwordx4 v[192:195], v[56:57], off offset:576
	s_waitcnt vmcnt(6) lgkmcnt(0)
; template <class Epi, class Sched, bool ALIGN_EPI = false, bool SP2 = false, bool HALO = false>
; __device__ __forceinline__ void gemm_phase(PG8_LAS unsigned char* lds, const Gemm g, const Sched& S, const Epi& E, const int wave0) {
;     ...
;         if (!has_next) break;
;     __device__ __forceinline__ void operator()(const pg8::f32x4 (&acc)[2][2][4][2], const pg8::Unit& u, int wr, int wc, int fr, int fq) const {
;         const int col0 = u.pn * 256 + wc * 32 + 4 * fq;
; #pragma unroll
;         for (int ai = 0; ai < 2; ++ai)
; #pragma unroll
;             for (int m = 0; m < 4; ++m) {
;                 const int r = row_off + u.pm * 256 + ai * 128 + wr * 64 + m * 16 + fr;
;                 const bool lat = r < ML; const int bi = lat ? (r >> 13) : 4;
;                 const size_t off = lat ? (size_t)r * 1024 : (size_t)(r - ML) * 1024;
;                 const float* bp = (lat ? base_lat : base_ctx) + off + col0; float* op = (lat ? out_lat : out_ctx) + off + col0;
;                 const float* gp = gate + bi * 6144 + col0;
; #pragma unroll
;                 for (int bj = 0; bj < 2; ++bj)
; #pragma unroll
;                     for (int n = 0; n < 2; ++n) {
;                         const pg8::f32x4 g4 = *(const pg8::f32x4*)(gp + bj * 128 + n * 16), b4 = *(const pg8::f32x4*)(bp + bj * 128 + n * 16);
;                         *(pg8::f32x4*)(op + bj * 128 + n * 16) = b4 + g4 * acc[ai][bj][m][n];
;                     }
;             }
;     }
	v_pk_fma_f32 v[46:47], v[46:47], v[166:167], v[170:171]
	v_pk_fma_f32 v[44:45], v[44:45], v[164:165], v[168:169]
	global_store_dwordx4 v[58:59], v[44:47], off
	s_waitcnt vmcnt(5) lgkmcnt(0)
	v_pk_fma_f32 v[42:43], v[42:43], v[174:175], v[178:179]
	v_pk_fma_f32 v[40:41], v[40:41], v[172:173], v[176:177]
	global_store_dwordx4 v[58:59], v[40:43], off offset:64
	s_waitcnt vmcnt(4) lgkmcnt(0)
	v_pk_fma_f32 v[38:39], v[38:39], v[182:183], v[186:187]
	v_pk_fma_f32 v[36:37], v[36:37], v[180:181], v[184:185]
	global_store_dwordx4 v[58:59], v[36:39], off offset:512
	s_waitcnt vmcnt(3) lgkmcnt(0)
	v_pk_fma_f32 v[34:35], v[34:35], v[190:191], v[194:195]
	v_pk_fma_f32 v[32:33], v[32:33], v[188:189], v[192:193]
	global_store_dwordx4 v[58:59], v[32:35], off offset:576
	s_nop 1
	v_add_u32_e32 v32, 0xa0, v142
	v_min_i32_e32 v33, 0x8000, v32
	v_cmp_gt_i32_e32 vcc, s97, v32
	v_ashrrev_i32_e32 v36, 13, v33
	v_ashrrev_i32_e32 v33, 31, v32
	v_add_u32_e32 v34, 0xffff80a0, v142
	v_cndmask_b32_e32 v33, 0, v33, vcc
	v_cndmask_b32_e32 v32, v34, v32, vcc
	v_cndmask_b32_e32 v35, v140, v141, vcc
	v_cndmask_b32_e32 v34, v143, v144, vcc
	v_lshlrev_b64 v[32:33], 12, v[32:33]
	v_lshl_add_u64 v[34:35], v[34:35], 0, v[32:33]
	v_lshl_add_u64 v[40:41], v[34:35], 0, v[134:135]
	v_cndmask_b32_e32 v35, v145, v146, vcc
	v_cndmask_b32_e32 v34, v147, v148, vcc
	v_lshl_add_u64 v[32:33], v[34:35], 0, v[32:33]
	v_lshl_add_u64 v[42:43], v[32:33], 0, v[134:135]
	v_mul_i32_i24_e32 v32, 0x1800, v36
	v_ashrrev_i32_e32 v33, 31, v32
	v_lshl_add_u64 v[32:33], v[32:33], 2, s[6:7]
	v_lshl_add_u64 v[44:45], v[32:33], 0, v[134:135]
	global_load_dwordx4 v[164:167], v[44:45], off
	global_load_dwordx4 v[168:171], v[40:41], off
	global_load_dwordx4 v[172:175], v[44:45], off offset:64
	global_load_dwordx4 v[176:179], v[40:41], off offset:64
	global_load_dwordx4 v[180:183], v[44:45], off offset:512
	global_load_dwordx4 v[184:187], v[40:41], off offset:512
	global_load_dwordx4 v[188:191], v[44:45], off offset:576
	global_load_dwordx4 v[192:195], v[40:41], off offset:576
	s_waitcnt vmcnt(6) lgkmcnt(0)
	v_pk_fma_f32 v[30:31], v[30:31], v[166:167], v[170:171]
	v_pk_fma_f32 v[28:29], v[28:29], v[164:165], v[168:169]
	global_store_dwordx4 v[42:43], v[28:31], off
	s_waitcnt vmcnt(5) lgkmcnt(0)
	v_pk_fma_f32 v[26:27], v[26:27], v[174:175], v[178:179]
	v_pk_fma_f32 v[24:25], v[24:25], v[172:173], v[176:177]
	global_store_dwordx4 v[42:43], v[24:27], off offset:64
	s_waitcnt vmcnt(4) lgkmcnt(0)
	v_pk_fma_f32 v[22:23], v[22:23], v[182:183], v[186:187]
	v_pk_fma_f32 v[20:21], v[20:21], v[180:181], v[184:185]
	global_store_dwordx4 v[42:43], v[20:23], off offset:512
	s_waitcnt vmcnt(3) lgkmcnt(0)
	v_pk_fma_f32 v[18:19], v[18:19], v[190:191], v[194:195]
	v_pk_fma_f32 v[16:17], v[16:17], v[188:189], v[192:193]
	global_store_dwordx4 v[42:43], v[16:19], off offset:576
	s_nop 1
	v_add_u32_e32 v16, 0xb0, v142
	v_min_i32_e32 v17, 0x8000, v16
	v_cmp_gt_i32_e32 vcc, s97, v16
	v_ashrrev_i32_e32 v20, 13, v17
	v_ashrrev_i32_e32 v17, 31, v16
	v_add_u32_e32 v18, 0xffff80b0, v142
	v_cndmask_b32_e32 v17, 0, v17, vcc
	v_cndmask_b32_e32 v16, v18, v16, vcc
	v_cndmask_b32_e32 v19, v140, v141, vcc
	v_cndmask_b32_e32 v18, v143, v144, vcc
	v_lshlrev_b64 v[16:17], 12, v[16:17]
	v_lshl_add_u64 v[18:19], v[18:19], 0, v[16:17]
	v_lshl_add_u64 v[24:25], v[18:19], 0, v[134:135]
	v_cndmask_b32_e32 v19, v145, v146, vcc
	v_cndmask_b32_e32 v18, v147, v148, vcc
	v_lshl_add_u64 v[16:17], v[18:19], 0, v[16:17]
	v_lshl_add_u64 v[26:27], v[16:17], 0, v[134:135]
	v_mul_i32_i24_e32 v16, 0x1800, v20
	v_ashrrev_i32_e32 v17, 31, v16
	v_lshl_add_u64 v[16:17], v[16:17], 2, s[6:7]
	v_lshl_add_u64 v[28:29], v[16:17], 0, v[134:135]
	global_load_dwordx4 v[164:167], v[28:29], off
	global_load_dwordx4 v[168:171], v[24:25], off
	global_load_dwordx4 v[172:175], v[28:29], off offset:64
	global_load_dwordx4 v[176:179], v[24:25], off offset:64
	global_load_dwordx4 v[180:183], v[28:29], off offset:512
	global_load_dwordx4 v[184:187], v[24:25], off offset:512
	global_load_dwordx4 v[188:191], v[28:29], off offset:576
	global_load_dwordx4 v[192:195], v[24:25], off offset:576
	s_andn2_b64 vcc, exec, s[38:39]
	s_waitcnt vmcnt(6) lgkmcnt(0)
	v_pk_fma_f32 v[14:15], v[14:15], v[166:167], v[170:171]
	v_pk_fma_f32 v[12:13], v[12:13], v[164:165], v[168:169]
	global_store_dwordx4 v[26:27], v[12:15], off
	s_waitcnt vmcnt(5) lgkmcnt(0)
	v_pk_fma_f32 v[10:11], v[10:11], v[174:175], v[178:179]
	v_pk_fma_f32 v[8:9], v[8:9], v[172:173], v[176:177]
	global_store_dwordx4 v[26:27], v[8:11], off offset:64
	s_waitcnt vmcnt(4) lgkmcnt(0)
	v_pk_fma_f32 v[6:7], v[6:7], v[182:183], v[186:187]
	v_pk_fma_f32 v[4:5], v[4:5], v[180:181], v[184:185]
	global_store_dwordx4 v[26:27], v[4:7], off offset:512
	s_waitcnt vmcnt(3) lgkmcnt(0)
	v_pk_fma_f32 v[2:3], v[2:3], v[190:191], v[194:195]
	v_pk_fma_f32 v[0:1], v[0:1], v[188:189], v[192:193]
	global_store_dwordx4 v[26:27], v[0:3], off offset:576
	s_cbranch_vccnz .LBB0_914
	s_andn2_b64 vcc, exec, s[4:5]
	s_cbranch_vccnz .LBB0_913
	s_barrier
	s_branch .LBB0_913

;     __device__ __forceinline__ void operator()(const pg8::f32x4 (&acc)[2][2][4][2], const pg8::Unit& u, int wr, int wc, int fr, int fq) const {
;         const int col0 = u.pn * 256 + wc * 32 + 4 * fq;
; #pragma unroll
;         for (int ai = 0; ai < 2; ++ai)
; #pragma unroll
;             for (int m = 0; m < 4; ++m) {
;                 const int r = row_off + u.pm * 256 + ai * 128 + wr * 64 + m * 16 + fr;
;                 const bool lat = r < ML; const int bi = lat ? (r >> 13) : 4;
;                 const size_t off = lat ? (size_t)r * 1024 : (size_t)(r - ML) * 1024;
;                 const float* bp = (lat ? base_lat : base_ctx) + off + col0; float* op = (lat ? out_lat : out_ctx) + off + col0;
;                 const float* gp = gate + bi * 6144 + col0;
; #pragma unroll
;                 for (int bj = 0; bj < 2; ++bj)
; #pragma unroll
;                     for (int n = 0; n < 2; ++n) {
;                         const pg8::f32x4 g4 = *(const pg8::f32x4*)(gp + bj * 128 + n * 16), b4 = *(const pg8::f32x4*)(bp + bj * 128 + n * 16);
;                         *(pg8::f32x4*)(op + bj * 128 + n * 16) = b4 + g4 * acc[ai][bj][m][n];
;                     }
;             }
;     }
.LBB0_1174:
	v_lshl_add_u32 v143, s75, 8, v136
	v_min_i32_e32 v140, 0x8000, v143
	v_readlane_b32 s12, v254, 35
	v_cmp_gt_i32_e32 vcc, s97, v143
	v_ashrrev_i32_e32 v152, 13, v140
	v_ashrrev_i32_e32 v140, 31, v143
	v_add_u32_e32 v141, 0xffff8000, v143
	v_readlane_b32 s13, v254, 36
	v_lshl_or_b32 v134, s74, 8, v138
	v_cndmask_b32_e32 v147, 0, v140, vcc
	v_cndmask_b32_e32 v146, v141, v143, vcc
	v_mov_b32_e32 v142, s66
	v_mov_b32_e32 v140, s13
	v_mov_b32_e32 v144, s65
	v_mov_b32_e32 v141, s12
	v_ashrrev_i32_e32 v135, 31, v134
	v_cndmask_b32_e32 v149, v142, v140, vcc
	v_cndmask_b32_e32 v148, v144, v141, vcc
	v_lshlrev_b64 v[150:151], 12, v[146:147]
	v_lshl_add_u64 v[146:147], v[148:149], 0, v[150:151]
	v_lshlrev_b64 v[134:135], 2, v[134:135]
	v_lshl_add_u64 v[156:157], v[146:147], 0, v[134:135]
	v_mov_b32_e32 v145, s68
	v_mov_b32_e32 v146, s67
	v_cndmask_b32_e32 v149, v145, v140, vcc
	v_cndmask_b32_e32 v148, v146, v141, vcc
	v_lshl_add_u64 v[148:149], v[148:149], 0, v[150:151]
	v_lshl_add_u64 v[158:159], v[148:149], 0, v[134:135]
	v_mul_i32_i24_e32 v148, 0x1800, v152
	v_ashrrev_i32_e32 v149, 31, v148
	v_lshl_add_u64 v[148:149], v[148:149], 2, s[4:5]
	v_lshl_add_u64 v[160:161], v[148:149], 0, v[134:135]
	global_load_dwordx4 v[164:167], v[160:161], off
	global_load_dwordx4 v[168:171], v[156:157], off
	global_load_dwordx4 v[172:175], v[160:161], off offset:64
	global_load_dwordx4 v[176:179], v[156:157], off offset:64
	global_load_dwordx4 v[180:183], v[160:161], off offset:512
	global_load_dwordx4 v[184:187], v[156:157], off offset:512
	global_load_dwordx4 v[188:191], v[160:161], off offset:576
	global_load_dwordx4 v[192:195], v[156:157], off offset:576
	s_mov_b64 s[36:37], -1
	s_waitcnt vmcnt(6) lgkmcnt(0)
	v_pk_fma_f32 v[126:127], v[126:127], v[166:167], v[170:171]
	v_pk_fma_f32 v[124:125], v[124:125], v[164:165], v[168:169]
	global_store_dwordx4 v[158:159], v[124:127], off
	s_waitcnt vmcnt(5) lgkmcnt(0)
	v_pk_fma_f32 v[122:123], v[122:123], v[174:175], v[178:179]
	v_pk_fma_f32 v[120:121], v[120:121], v[172:173], v[176:177]
	global_store_dwordx4 v[158:159], v[120:123], off offset:64
	s_waitcnt vmcnt(4) lgkmcnt(0)
	v_pk_fma_f32 v[118:119], v[118:119], v[182:183], v[186:187]
	v_pk_fma_f32 v[116:117], v[116:117], v[180:181], v[184:185]
	global_store_dwordx4 v[158:159], v[116:119], off offset:512
	s_waitcnt vmcnt(3) lgkmcnt(0)
	v_pk_fma_f32 v[114:115], v[114:115], v[190:191], v[194:195]
	v_pk_fma_f32 v[112:113], v[112:113], v[188:189], v[192:193]
	global_store_dwordx4 v[158:159], v[112:115], off offset:576
	s_nop 1
	v_or_b32_e32 v112, 16, v143
	v_min_i32_e32 v113, 0x8000, v112
	v_cmp_gt_i32_e32 vcc, s97, v112
	v_ashrrev_i32_e32 v116, 13, v113
	v_ashrrev_i32_e32 v113, 31, v112
	v_add_u32_e32 v114, 0xffff8010, v143
	v_cndmask_b32_e32 v113, 0, v113, vcc
	v_cndmask_b32_e32 v112, v114, v112, vcc
	v_cndmask_b32_e32 v115, v142, v140, vcc
	v_cndmask_b32_e32 v114, v144, v141, vcc
	v_lshlrev_b64 v[112:113], 12, v[112:113]
	v_lshl_add_u64 v[114:115], v[114:115], 0, v[112:113]
	v_lshl_add_u64 v[120:121], v[114:115], 0, v[134:135]
	v_cndmask_b32_e32 v115, v145, v140, vcc
	v_cndmask_b32_e32 v114, v146, v141, vcc
	v_lshl_add_u64 v[112:113], v[114:115], 0, v[112:113]
	v_lshl_add_u64 v[122:123], v[112:113], 0, v[134:135]
	v_mul_i32_i24_e32 v112, 0x1800, v116
	v_ashrrev_i32_e32 v113, 31, v112
	v_lshl_add_u64 v[112:113], v[112:113], 2, s[4:5]
	v_lshl_add_u64 v[124:125], v[112:113], 0, v[134:135]
	global_load_dwordx4 v[164:167], v[124:125], off
	global_load_dwordx4 v[168:171], v[120:121], off
	global_load_dwordx4 v[172:175], v[124:125], off offset:64
	global_load_dwordx4 v[176:179], v[120:121], off offset:64
	global_load_dwordx4 v[180:183], v[124:125], off offset:512
	global_load_dwordx4 v[184:187], v[120:121], off offset:512
	global_load_dwordx4 v[188:191], v[124:125], off offset:576
	global_load_dwordx4 v[192:195], v[120:121], off offset:576
	s_waitcnt vmcnt(6) lgkmcnt(0)
	v_pk_fma_f32 v[110:111], v[110:111], v[166:167], v[170:171]
	v_pk_fma_f32 v[108:109], v[108:109], v[164:165], v[168:169]
	global_store_dwordx4 v[122:123], v[108:111], off
	s_waitcnt vmcnt(5) lgkmcnt(0)
	v_pk_fma_f32 v[106:107], v[106:107], v[174:175], v[178:179]
	v_pk_fma_f32 v[104:105], v[104:105], v[172:173], v[176:177]
	global_store_dwordx4 v[122:123], v[104:107], off offset:64
	s_waitcnt vmcnt(4) lgkmcnt(0)
	v_pk_fma_f32 v[102:103], v[102:103], v[182:183], v[186:187]
	v_pk_fma_f32 v[100:101], v[100:101], v[180:181], v[184:185]
	global_store_dwordx4 v[122:123], v[100:103], off offset:512
	s_waitcnt vmcnt(3) lgkmcnt(0)
	v_pk_fma_f32 v[98:99], v[98:99], v[190:191], v[194:195]
	v_pk_fma_f32 v[96:97], v[96:97], v[188:189], v[192:193]
	global_store_dwordx4 v[122:123], v[96:99], off offset:576
	s_nop 1
	v_or_b32_e32 v96, 32, v143
	v_min_i32_e32 v97, 0x8000, v96
	v_cmp_gt_i32_e32 vcc, s97, v96
	v_ashrrev_i32_e32 v100, 13, v97
	v_ashrrev_i32_e32 v97, 31, v96
	v_add_u32_e32 v98, 0xffff8020, v143
	v_cndmask_b32_e32 v97, 0, v97, vcc
	v_cndmask_b32_e32 v96, v98, v96, vcc
	v_cndmask_b32_e32 v99, v142, v140, vcc
	v_cndmask_b32_e32 v98, v144, v141, vcc
	v_lshlrev_b64 v[96:97], 12, v[96:97]
	v_lshl_add_u64 v[98:99], v[98:99], 0, v[96:97]
	v_lshl_add_u64 v[104:105], v[98:99], 0, v[134:135]
	v_cndmask_b32_e32 v99, v145, v140, vcc
	v_cndmask_b32_e32 v98, v146, v141, vcc
	v_lshl_add_u64 v[96:97], v[98:99], 0, v[96:97]
	v_lshl_add_u64 v[106:107], v[96:97], 0, v[134:135]
	v_mul_i32_i24_e32 v96, 0x1800, v100
	v_ashrrev_i32_e32 v97, 31, v96
	v_lshl_add_u64 v[96:97], v[96:97], 2, s[4:5]
	v_lshl_add_u64 v[108:109], v[96:97], 0, v[134:135]
	global_load_dwordx4 v[164:167], v[108:109], off
	global_load_dwordx4 v[168:171], v[104:105], off
	global_load_dwordx4 v[172:175], v[108:109], off offset:64
	global_load_dwordx4 v[176:179], v[104:105], off offset:64
	global_load_dwordx4 v[180:183], v[108:109], off offset:512
	global_load_dwordx4 v[184:187], v[104:105], off offset:512
	global_load_dwordx4 v[188:191], v[108:109], off offset:576
	global_load_dwordx4 v[192:195], v[104:105], off offset:576
	s_waitcnt vmcnt(6) lgkmcnt(0)
;     __device__ __forceinline__ void operator()(const pg8::f32x4 (&acc)[2][2][4][2], const pg8::Unit& u, int wr, int wc, int fr, int fq) const {
;         const int col0 = u.pn * 256 + wc * 32 + 4 * fq;
; #pragma unroll
;         for (int ai = 0; ai < 2; ++ai)
; #pragma unroll
;             for (int m = 0; m < 4; ++m) {
;                 const int r = row_off + u.pm * 256 + ai * 128 + wr * 64 + m * 16 + fr;
;                 const bool lat = r < ML; const int bi = lat ? (r >> 13) : 4;
;                 const size_t off = lat ? (size_t)r * 1024 : (size_t)(r - ML) * 1024;
;                 const float* bp = (lat ? base_lat : base_ctx) + off + col0; float* op = (lat ? out_lat : out_ctx) + off + col0;
;                 const float* gp = gate + bi * 6144 + col0;
; #pragma unroll
;                 for (int bj = 0; bj < 2; ++bj)
; #pragma unroll
;                     for (int n = 0; n < 2; ++n) {
;                         const pg8::f32x4 g4 = *(const pg8::f32x4*)(gp + bj * 128 + n * 16), b4 = *(const pg8::f32x4*)(bp + bj * 128 + n * 16);
;                         *(pg8::f32x4*)(op + bj * 128 + n * 16) = b4 + g4 * acc[ai][bj][m][n];
;                     }
;             }
;     }
	v_pk_fma_f32 v[94:95], v[94:95], v[166:167], v[170:171]
	v_pk_fma_f32 v[92:93], v[92:93], v[164:165], v[168:169]
	global_store_dwordx4 v[106:107], v[92:95], off
	s_waitcnt vmcnt(5) lgkmcnt(0)
	v_pk_fma_f32 v[90:91], v[90:91], v[174:175], v[178:179]
	v_pk_fma_f32 v[88:89], v[88:89], v[172:173], v[176:177]
	global_store_dwordx4 v[106:107], v[88:91], off offset:64
	s_waitcnt vmcnt(4) lgkmcnt(0)
	v_pk_fma_f32 v[86:87], v[86:87], v[182:183], v[186:187]
	v_pk_fma_f32 v[84:85], v[84:85], v[180:181], v[184:185]
	global_store_dwordx4 v[106:107], v[84:87], off offset:512
	s_waitcnt vmcnt(3) lgkmcnt(0)
	v_pk_fma_f32 v[82:83], v[82:83], v[190:191], v[194:195]
	v_pk_fma_f32 v[80:81], v[80:81], v[188:189], v[192:193]
	global_store_dwordx4 v[106:107], v[80:83], off offset:576
	s_nop 1
	v_or_b32_e32 v80, 48, v143
	v_min_i32_e32 v81, 0x8000, v80
	v_cmp_gt_i32_e32 vcc, s97, v80
	v_ashrrev_i32_e32 v84, 13, v81
	v_ashrrev_i32_e32 v81, 31, v80
	v_add_u32_e32 v82, 0xffff8030, v143
	v_cndmask_b32_e32 v81, 0, v81, vcc
	v_cndmask_b32_e32 v80, v82, v80, vcc
	v_cndmask_b32_e32 v83, v142, v140, vcc
	v_cndmask_b32_e32 v82, v144, v141, vcc
	v_lshlrev_b64 v[80:81], 12, v[80:81]
	v_lshl_add_u64 v[82:83], v[82:83], 0, v[80:81]
	v_lshl_add_u64 v[88:89], v[82:83], 0, v[134:135]
	v_cndmask_b32_e32 v83, v145, v140, vcc
	v_cndmask_b32_e32 v82, v146, v141, vcc
	v_lshl_add_u64 v[80:81], v[82:83], 0, v[80:81]
	v_lshl_add_u64 v[90:91], v[80:81], 0, v[134:135]
	v_mul_i32_i24_e32 v80, 0x1800, v84
	v_ashrrev_i32_e32 v81, 31, v80
	v_lshl_add_u64 v[80:81], v[80:81], 2, s[4:5]
	v_lshl_add_u64 v[92:93], v[80:81], 0, v[134:135]
	global_load_dwordx4 v[164:167], v[92:93], off
	global_load_dwordx4 v[168:171], v[88:89], off
	global_load_dwordx4 v[172:175], v[92:93], off offset:64
	global_load_dwordx4 v[176:179], v[88:89], off offset:64
	global_load_dwordx4 v[180:183], v[92:93], off offset:512
	global_load_dwordx4 v[184:187], v[88:89], off offset:512
	global_load_dwordx4 v[188:191], v[92:93], off offset:576
	global_load_dwordx4 v[192:195], v[88:89], off offset:576
	s_waitcnt vmcnt(6) lgkmcnt(0)
	v_pk_fma_f32 v[78:79], v[78:79], v[166:167], v[170:171]
	v_pk_fma_f32 v[76:77], v[76:77], v[164:165], v[168:169]
	global_store_dwordx4 v[90:91], v[76:79], off
	s_waitcnt vmcnt(5) lgkmcnt(0)
	v_pk_fma_f32 v[74:75], v[74:75], v[174:175], v[178:179]
	v_pk_fma_f32 v[72:73], v[72:73], v[172:173], v[176:177]
	global_store_dwordx4 v[90:91], v[72:75], off offset:64
	s_waitcnt vmcnt(4) lgkmcnt(0)
	v_pk_fma_f32 v[70:71], v[70:71], v[182:183], v[186:187]
	v_pk_fma_f32 v[68:69], v[68:69], v[180:181], v[184:185]
	global_store_dwordx4 v[90:91], v[68:71], off offset:512
	s_waitcnt vmcnt(3) lgkmcnt(0)
	v_pk_fma_f32 v[66:67], v[66:67], v[190:191], v[194:195]
	v_pk_fma_f32 v[64:65], v[64:65], v[188:189], v[192:193]
	global_store_dwordx4 v[90:91], v[64:67], off offset:576
	s_nop 1
	v_add_u32_e32 v64, 0x80, v143
	v_min_i32_e32 v65, 0x8000, v64
	v_cmp_gt_i32_e32 vcc, s97, v64
	v_ashrrev_i32_e32 v68, 13, v65
	v_ashrrev_i32_e32 v65, 31, v64
	v_add_u32_e32 v66, 0xffff8080, v143
	v_cndmask_b32_e32 v65, 0, v65, vcc
	v_cndmask_b32_e32 v64, v66, v64, vcc
	v_cndmask_b32_e32 v67, v142, v140, vcc
	v_cndmask_b32_e32 v66, v144, v141, vcc
	v_lshlrev_b64 v[64:65], 12, v[64:65]
	v_lshl_add_u64 v[66:67], v[66:67], 0, v[64:65]
	v_lshl_add_u64 v[72:73], v[66:67], 0, v[134:135]
	v_cndmask_b32_e32 v67, v145, v140, vcc
	v_cndmask_b32_e32 v66, v146, v141, vcc
	v_lshl_add_u64 v[64:65], v[66:67], 0, v[64:65]
	v_lshl_add_u64 v[74:75], v[64:65], 0, v[134:135]
	v_mul_i32_i24_e32 v64, 0x1800, v68
	v_ashrrev_i32_e32 v65, 31, v64
	v_lshl_add_u64 v[64:65], v[64:65], 2, s[4:5]
	v_lshl_add_u64 v[76:77], v[64:65], 0, v[134:135]
	global_load_dwordx4 v[164:167], v[76:77], off
	global_load_dwordx4 v[168:171], v[72:73], off
	global_load_dwordx4 v[172:175], v[76:77], off offset:64
	global_load_dwordx4 v[176:179], v[72:73], off offset:64
	global_load_dwordx4 v[180:183], v[76:77], off offset:512
	global_load_dwordx4 v[184:187], v[72:73], off offset:512
	global_load_dwordx4 v[188:191], v[76:77], off offset:576
	global_load_dwordx4 v[192:195], v[72:73], off offset:576
	s_waitcnt vmcnt(6) lgkmcnt(0)
	v_pk_fma_f32 v[62:63], v[62:63], v[166:167], v[170:171]
	v_pk_fma_f32 v[60:61], v[60:61], v[164:165], v[168:169]
	global_store_dwordx4 v[74:75], v[60:63], off
	s_waitcnt vmcnt(5) lgkmcnt(0)
	v_pk_fma_f32 v[58:59], v[58:59], v[174:175], v[178:179]
	v_pk_fma_f32 v[56:57], v[56:57], v[172:173], v[176:177]
	global_store_dwordx4 v[74:75], v[56:59], off offset:64
	s_waitcnt vmcnt(4) lgkmcnt(0)
	v_pk_fma_f32 v[54:55], v[54:55], v[182:183], v[186:187]
	v_pk_fma_f32 v[52:53], v[52:53], v[180:181], v[184:185]
	global_store_dwordx4 v[74:75], v[52:55], off offset:512
	s_waitcnt vmcnt(3) lgkmcnt(0)
	v_pk_fma_f32 v[50:51], v[50:51], v[190:191], v[194:195]
	v_pk_fma_f32 v[48:49], v[48:49], v[188:189], v[192:193]
	global_store_dwordx4 v[74:75], v[48:51], off offset:576
	s_nop 1
	v_add_u32_e32 v48, 0x90, v143
	v_min_i32_e32 v49, 0x8000, v48
	v_cmp_gt_i32_e32 vcc, s97, v48
	v_ashrrev_i32_e32 v52, 13, v49
	v_ashrrev_i32_e32 v49, 31, v48
	v_add_u32_e32 v50, 0xffff8090, v143
	v_cndmask_b32_e32 v49, 0, v49, vcc
	v_cndmask_b32_e32 v48, v50, v48, vcc
	v_cndmask_b32_e32 v51, v142, v140, vcc
	v_cndmask_b32_e32 v50, v144, v141, vcc
	v_lshlrev_b64 v[48:49], 12, v[48:49]
	v_lshl_add_u64 v[50:51], v[50:51], 0, v[48:49]
	v_lshl_add_u64 v[56:57], v[50:51], 0, v[134:135]
	v_cndmask_b32_e32 v51, v145, v140, vcc
	v_cndmask_b32_e32 v50, v146, v141, vcc
	v_lshl_add_u64 v[48:49], v[50:51], 0, v[48:49]
	v_lshl_add_u64 v[58:59], v[48:49], 0, v[134:135]
	v_mul_i32_i24_e32 v48, 0x1800, v52
	v_ashrrev_i32_e32 v49, 31, v48
	v_lshl_add_u64 v[48:49], v[48:49], 2, s[4:5]
	v_lshl_add_u64 v[60:61], v[48:49], 0, v[134:135]
	global_load_dwordx4 v[164:167], v[60:61], off
	global_load_dwordx4 v[168:171], v[56:57], off
	global_load_dwordx4 v[172:175], v[60:61], off offset:64
	global_load_dwordx4 v[176:179], v[56:57], off offset:64
	global_load_dwordx4 v[180:183], v[60:61], off offset:512
	global_load_dwordx4 v[184:187], v[56:57], off offset:512
	global_load_dwordx4 v[188:191], v[60:61], off offset:576
	global_load_dwordx4 v[192:195], v[56:57], off offset:576
	s_waitcnt vmcnt(6) lgkmcnt(0)
; template <class Epi, class Sched, bool ALIGN_EPI = false, bool SP2 = false, bool HALO = false>
; __device__ __forceinline__ void gemm_phase(PG8_LAS unsigned char* lds, const Gemm g, const Sched& S, const Epi& E, const int wave0) {
;     ...
;         if (!has_next) break;
;     __device__ __forceinline__ void operator()(const pg8::f32x4 (&acc)[2][2][4][2], const pg8::Unit& u, int wr, int wc, int fr, int fq) const {
;         const int col0 = u.pn * 256 + wc * 32 + 4 * fq;
; #pragma unroll
;         for (int ai = 0; ai < 2; ++ai)
; #pragma unroll
;             for (int m = 0; m < 4; ++m) {
;                 const int r = row_off + u.pm * 256 + ai * 128 + wr * 64 + m * 16 + fr;
;                 const bool lat = r < ML; const int bi = lat ? (r >> 13) : 4;
;                 const size_t off = lat ? (size_t)r * 1024 : (size_t)(r - ML) * 1024;
;                 const float* bp = (lat ? base_lat : base_ctx) + off + col0; float* op = (lat ? out_lat : out_ctx) + off + col0;
;                 const float* gp = gate + bi * 6144 + col0;
; #pragma unroll
;                 for (int bj = 0; bj < 2; ++bj)
; #pragma unroll
;                     for (int n = 0; n < 2; ++n) {
;                         const pg8::f32x4 g4 = *(const pg8::f32x4*)(gp + bj * 128 + n * 16), b4 = *(const pg8::f32x4*)(bp + bj * 128 + n * 16);
;                         *(pg8::f32x4*)(op + bj * 128 + n * 16) = b4 + g4 * acc[ai][bj][m][n];
;                     }
;             }
;     }
	v_pk_fma_f32 v[46:47], v[46:47], v[166:167], v[170:171]
	v_pk_fma_f32 v[44:45], v[44:45], v[164:165], v[168:169]
	global_store_dwordx4 v[58:59], v[44:47], off
	s_waitcnt vmcnt(5) lgkmcnt(0)
	v_pk_fma_f32 v[42:43], v[42:43], v[174:175], v[178:179]
	v_pk_fma_f32 v[40:41], v[40:41], v[172:173], v[176:177]
	global_store_dwordx4 v[58:59], v[40:43], off offset:64
	s_waitcnt vmcnt(4) lgkmcnt(0)
	v_pk_fma_f32 v[38:39], v[38:39], v[182:183], v[186:187]
	v_pk_fma_f32 v[36:37], v[36:37], v[180:181], v[184:185]
	global_store_dwordx4 v[58:59], v[36:39], off offset:512
	s_waitcnt vmcnt(3) lgkmcnt(0)
	v_pk_fma_f32 v[34:35], v[34:35], v[190:191], v[194:195]
	v_pk_fma_f32 v[32:33], v[32:33], v[188:189], v[192:193]
	global_store_dwordx4 v[58:59], v[32:35], off offset:576
	s_nop 1
	v_add_u32_e32 v32, 0xa0, v143
	v_min_i32_e32 v33, 0x8000, v32
	v_cmp_gt_i32_e32 vcc, s97, v32
	v_ashrrev_i32_e32 v36, 13, v33
	v_ashrrev_i32_e32 v33, 31, v32
	v_add_u32_e32 v34, 0xffff80a0, v143
	v_cndmask_b32_e32 v33, 0, v33, vcc
	v_cndmask_b32_e32 v32, v34, v32, vcc
	v_cndmask_b32_e32 v35, v142, v140, vcc
	v_cndmask_b32_e32 v34, v144, v141, vcc
	v_lshlrev_b64 v[32:33], 12, v[32:33]
	v_lshl_add_u64 v[34:35], v[34:35], 0, v[32:33]
	v_lshl_add_u64 v[40:41], v[34:35], 0, v[134:135]
	v_cndmask_b32_e32 v35, v145, v140, vcc
	v_cndmask_b32_e32 v34, v146, v141, vcc
	v_lshl_add_u64 v[32:33], v[34:35], 0, v[32:33]
	v_lshl_add_u64 v[42:43], v[32:33], 0, v[134:135]
	v_mul_i32_i24_e32 v32, 0x1800, v36
	v_ashrrev_i32_e32 v33, 31, v32
	v_lshl_add_u64 v[32:33], v[32:33], 2, s[4:5]
	v_lshl_add_u64 v[44:45], v[32:33], 0, v[134:135]
	global_load_dwordx4 v[164:167], v[44:45], off
	global_load_dwordx4 v[168:171], v[40:41], off
	global_load_dwordx4 v[172:175], v[44:45], off offset:64
	global_load_dwordx4 v[176:179], v[40:41], off offset:64
	global_load_dwordx4 v[180:183], v[44:45], off offset:512
	global_load_dwordx4 v[184:187], v[40:41], off offset:512
	global_load_dwordx4 v[188:191], v[44:45], off offset:576
	global_load_dwordx4 v[192:195], v[40:41], off offset:576
	s_waitcnt vmcnt(6) lgkmcnt(0)
	v_pk_fma_f32 v[30:31], v[30:31], v[166:167], v[170:171]
	v_pk_fma_f32 v[28:29], v[28:29], v[164:165], v[168:169]
	global_store_dwordx4 v[42:43], v[28:31], off
	s_waitcnt vmcnt(5) lgkmcnt(0)
	v_pk_fma_f32 v[26:27], v[26:27], v[174:175], v[178:179]
	v_pk_fma_f32 v[24:25], v[24:25], v[172:173], v[176:177]
	global_store_dwordx4 v[42:43], v[24:27], off offset:64
	s_waitcnt vmcnt(4) lgkmcnt(0)
	v_pk_fma_f32 v[22:23], v[22:23], v[182:183], v[186:187]
	v_pk_fma_f32 v[20:21], v[20:21], v[180:181], v[184:185]
	global_store_dwordx4 v[42:43], v[20:23], off offset:512
	s_waitcnt vmcnt(3) lgkmcnt(0)
	v_pk_fma_f32 v[18:19], v[18:19], v[190:191], v[194:195]
	v_pk_fma_f32 v[16:17], v[16:17], v[188:189], v[192:193]
	global_store_dwordx4 v[42:43], v[16:19], off offset:576
	s_nop 1
	v_add_u32_e32 v16, 0xb0, v143
	v_min_i32_e32 v17, 0x8000, v16
	v_cmp_gt_i32_e32 vcc, s97, v16
	v_ashrrev_i32_e32 v20, 13, v17
	v_ashrrev_i32_e32 v17, 31, v16
	v_add_u32_e32 v18, 0xffff80b0, v143
	v_cndmask_b32_e32 v17, 0, v17, vcc
	v_cndmask_b32_e32 v16, v18, v16, vcc
	v_cndmask_b32_e32 v19, v142, v140, vcc
	v_cndmask_b32_e32 v18, v144, v141, vcc
	v_lshlrev_b64 v[16:17], 12, v[16:17]
	v_lshl_add_u64 v[18:19], v[18:19], 0, v[16:17]
	v_lshl_add_u64 v[24:25], v[18:19], 0, v[134:135]
	v_cndmask_b32_e32 v19, v145, v140, vcc
	v_cndmask_b32_e32 v18, v146, v141, vcc
	v_lshl_add_u64 v[16:17], v[18:19], 0, v[16:17]
	v_lshl_add_u64 v[26:27], v[16:17], 0, v[134:135]
	v_mul_i32_i24_e32 v16, 0x1800, v20
	v_ashrrev_i32_e32 v17, 31, v16
	v_lshl_add_u64 v[16:17], v[16:17], 2, s[4:5]
	v_lshl_add_u64 v[28:29], v[16:17], 0, v[134:135]
	global_load_dwordx4 v[164:167], v[28:29], off
	global_load_dwordx4 v[168:171], v[24:25], off
	global_load_dwordx4 v[172:175], v[28:29], off offset:64
	global_load_dwordx4 v[176:179], v[24:25], off offset:64
	global_load_dwordx4 v[180:183], v[28:29], off offset:512
	global_load_dwordx4 v[184:187], v[24:25], off offset:512
	global_load_dwordx4 v[188:191], v[28:29], off offset:576
	global_load_dwordx4 v[192:195], v[24:25], off offset:576
	s_and_b64 vcc, exec, s[38:39]
	s_waitcnt vmcnt(6) lgkmcnt(0)
	v_pk_fma_f32 v[14:15], v[14:15], v[166:167], v[170:171]
	v_pk_fma_f32 v[12:13], v[12:13], v[164:165], v[168:169]
	global_store_dwordx4 v[26:27], v[12:15], off
	s_waitcnt vmcnt(5) lgkmcnt(0)
	v_pk_fma_f32 v[10:11], v[10:11], v[174:175], v[178:179]
	v_pk_fma_f32 v[8:9], v[8:9], v[172:173], v[176:177]
	global_store_dwordx4 v[26:27], v[8:11], off offset:64
	s_waitcnt vmcnt(4) lgkmcnt(0)
	v_pk_fma_f32 v[6:7], v[6:7], v[182:183], v[186:187]
	v_pk_fma_f32 v[4:5], v[4:5], v[180:181], v[184:185]
	global_store_dwordx4 v[26:27], v[4:7], off offset:512
	s_waitcnt vmcnt(3) lgkmcnt(0)
	v_pk_fma_f32 v[2:3], v[2:3], v[190:191], v[194:195]
	v_pk_fma_f32 v[0:1], v[0:1], v[188:189], v[192:193]
	global_store_dwordx4 v[26:27], v[0:3], off offset:576
	s_cbranch_vccnz .LBB0_1163
	s_andn2_b64 vcc, exec, s[2:3]
	s_cbranch_vccnz .LBB0_1162
	s_barrier
	s_branch .LBB0_1162
